# v35 + ssm_a: WA fragment ring 12 k-steps deep (24 loads in flight per wave), issued before the U-stage waits
# speedup vs baseline: 1.0008x; 1.0008x over previous
; #define LAS __attribute__((address_space(3)))
; __device__ __forceinline__ void ssm_stage_u(unsigned char* ws, LAS unsigned char* lds, int g, int cb, int hh, int tid) {
;     asm volatile("" : "+v"(tid));
;     const bf16* U = (const bf16*)(ws + AR_U);
;     u32x4 v[8];
; #pragma unroll
;     for (int r = 0; r < 8; ++r) { const int c = r * 512 + tid, jj = c >> 7, col = (c >> 1) & 63, part = c & 1;
;         v[r] = *(const u32x4*)(U + ((size_t)((cb * 64 + col) * 64 + hh * 32 + jj) * 512 + g * 16 + part * 8)); }
; #pragma unroll
;     for (int r = 0; r < 8; ++r) { const int c = r * 512 + tid; *(LAS u32x4*)(lds + SS_UB + c * 16) = v[r]; }
; }
; __device__ __forceinline__ void ssm_a_task(unsigned char* ws, LAS unsigned char* lds, int task, int tid) {
;     const int lane = tid & 63, wid = tid >> 6, rr = lane & 15, kk = lane >> 4;
;     const int g = task >> 3, cb = task & 7;
;     f32x4 acc[2][4];
; #pragma unroll
;     for (int a = 0; a < 2; ++a)
; #pragma unroll
;         for (int c = 0; c < 4; ++c) acc[a][c] = (f32x4){0.f, 0.f, 0.f, 0.f};
;     const bf16* WA = (const bf16*)(ws + WS_WA) + ((size_t)(g * 256 + wid * 32 + rr) * 1024 + 8 * kk);
;     for (int hh = 0; hh < 2; ++hh) {
;         ssm_stage_u(ws, lds, g, cb, hh, tid);
;         __syncthreads();
; #pragma unroll 4
;         for (int ks = 0; ks < 16; ++ks) {
;             bf16x8 bfr[4], afr[2];
; #pragma unroll
;             for (int a = 0; a < 2; ++a) afr[a] = *(const bf16x8*)(WA + (size_t)a * 16 * 1024 + (hh * 16 + ks) * 32);
.LBB0_603:
	s_ashr_i32 s16, s54, 3
	v_mov_b32_e32 v30, v44
	s_and_b32 s17, s54, 7
	s_lshl_b32 s14, s16, 4
	s_lshl_b32 s3, s17, 12
	v_lshlrev_b32_e32 v0, 5, v30
	s_ashr_i32 s15, s14, 31
	v_and_b32_e32 v0, 0xfc0, v0
	s_lshl_b64 s[14:15], s[14:15], 1
	v_or_b32_e32 v31, s3, v0
	v_ashrrev_i32_e32 v0, 7, v30
	v_add_u32_e32 v4, 0x200, v30
	s_add_u32 s34, s4, s14
	s_waitcnt vmcnt(1)
	v_lshlrev_b32_e32 v38, 4, v30
	v_add_u32_e32 v0, v31, v0
	v_ashrrev_i32_e32 v4, 7, v4
	v_add_u32_e32 v8, 0x400, v30
	s_addc_u32 s35, s5, s15
	v_and_b32_e32 v184, 16, v38
	v_ashrrev_i32_e32 v1, 31, v0
	v_add_u32_e32 v4, v31, v4
	v_ashrrev_i32_e32 v8, 7, v8
	v_add_u32_e32 v12, 0x600, v30
	v_lshl_add_u64 v[28:29], s[34:35], 0, v[184:185]
	v_lshlrev_b64 v[0:1], 10, v[0:1]
	v_ashrrev_i32_e32 v5, 31, v4
	v_add_u32_e32 v8, v31, v8
	v_ashrrev_i32_e32 v12, 7, v12
	v_add_u32_e32 v16, 0x800, v30
	v_lshl_add_u64 v[0:1], v[28:29], 0, v[0:1]
	v_lshlrev_b64 v[4:5], 10, v[4:5]
	v_ashrrev_i32_e32 v9, 31, v8
	v_add_u32_e32 v12, v31, v12
	v_ashrrev_i32_e32 v16, 7, v16
	v_add_u32_e32 v20, 0xa00, v30
	global_load_dwordx4 v[0:3], v[0:1], off
	v_lshl_add_u64 v[4:5], v[28:29], 0, v[4:5]
	v_lshlrev_b64 v[8:9], 10, v[8:9]
	v_ashrrev_i32_e32 v13, 31, v12
	v_add_u32_e32 v16, v31, v16
	v_ashrrev_i32_e32 v20, 7, v20
	v_add_u32_e32 v24, 0xc00, v30
	global_load_dwordx4 v[4:7], v[4:5], off
	v_lshl_add_u64 v[8:9], v[28:29], 0, v[8:9]
	v_lshlrev_b64 v[12:13], 10, v[12:13]
	v_ashrrev_i32_e32 v17, 31, v16
	v_add_u32_e32 v20, v31, v20
	v_ashrrev_i32_e32 v24, 7, v24
	v_add_u32_e32 v30, 0xe00, v30
	global_load_dwordx4 v[8:11], v[8:9], off
	v_lshl_add_u64 v[12:13], v[28:29], 0, v[12:13]
	v_lshlrev_b64 v[16:17], 10, v[16:17]
	v_ashrrev_i32_e32 v21, 31, v20
	v_add_u32_e32 v24, v31, v24
	v_ashrrev_i32_e32 v30, 7, v30
	global_load_dwordx4 v[12:15], v[12:13], off
	v_lshl_add_u64 v[16:17], v[28:29], 0, v[16:17]
	v_lshlrev_b64 v[20:21], 10, v[20:21]
	v_ashrrev_i32_e32 v25, 31, v24
	v_add_u32_e32 v30, v31, v30
	global_load_dwordx4 v[16:19], v[16:17], off
	v_lshl_add_u64 v[20:21], v[28:29], 0, v[20:21]
	v_lshlrev_b64 v[24:25], 10, v[24:25]
	v_ashrrev_i32_e32 v31, 31, v30
	global_load_dwordx4 v[20:23], v[20:21], off
	v_lshl_add_u64 v[24:25], v[28:29], 0, v[24:25]
	v_lshlrev_b64 v[30:31], 10, v[30:31]
	global_load_dwordx4 v[24:27], v[24:25], off
	v_lshl_add_u64 v[28:29], v[28:29], 0, v[30:31]
	global_load_dwordx4 v[28:31], v[28:29], off
	v_add_u32_e32 v38, 0, v38
	v_add_u32_e32 v38, 0x10000, v38
	s_mov_b32 s12, 0
	v_lshl_add_u32 v132, s16, 8, v46
	v_ashrrev_i32_e32 v133, 31, v132
	v_lshlrev_b64 v[132:133], 11, v[132:133]
	v_lshl_add_u64 v[40:41], v[34:35], 0, v[132:133]
	v_add_co_u32_e32 v164, vcc, 0xffff8000, v40
	s_nop 1
	v_addc_co_u32_e32 v165, vcc, -1, v41, vcc
	global_load_dwordx4 v[80:83], v[40:41], off offset:-192
	global_load_dwordx4 v[84:87], v[164:165], off offset:-192
	global_load_dwordx4 v[88:91], v[40:41], off offset:-128
	global_load_dwordx4 v[92:95], v[164:165], off offset:-128
	global_load_dwordx4 v[96:99], v[40:41], off offset:-64
	global_load_dwordx4 v[100:103], v[164:165], off offset:-64
	global_load_dwordx4 v[104:107], v[40:41], off offset:0
	global_load_dwordx4 v[108:111], v[164:165], off offset:0
	global_load_dwordx4 v[112:115], v[40:41], off offset:64
	global_load_dwordx4 v[116:119], v[164:165], off offset:64
	global_load_dwordx4 v[120:123], v[40:41], off offset:128
	global_load_dwordx4 v[124:127], v[164:165], off offset:128
	global_load_dwordx4 v[128:131], v[40:41], off offset:192
	global_load_dwordx4 v[168:171], v[164:165], off offset:192
	global_load_dwordx4 v[172:175], v[40:41], off offset:256
	global_load_dwordx4 v[176:179], v[164:165], off offset:256
	global_load_dwordx4 v[180:183], v[40:41], off offset:320
	global_load_dwordx4 v[186:189], v[164:165], off offset:320
	global_load_dwordx4 v[190:193], v[40:41], off offset:384
	global_load_dwordx4 v[194:197], v[164:165], off offset:384
	global_load_dwordx4 v[198:201], v[40:41], off offset:448
	global_load_dwordx4 v[202:205], v[164:165], off offset:448
	global_load_dwordx4 v[206:209], v[40:41], off offset:512
	global_load_dwordx4 v[210:213], v[164:165], off offset:512
	s_waitcnt vmcnt(31)
	ds_write_b128 v38, v[0:3]
	s_waitcnt vmcnt(30)
	ds_write_b128 v38, v[4:7] offset:8192
	s_waitcnt vmcnt(29)
	ds_write_b128 v38, v[8:11] offset:16384
	s_waitcnt vmcnt(28)
	ds_write_b128 v38, v[12:15] offset:24576
	s_waitcnt vmcnt(27)
	ds_write_b128 v38, v[16:19] offset:32768
	s_waitcnt vmcnt(26)
	ds_write_b128 v38, v[20:23] offset:40960
	s_waitcnt vmcnt(25)
	ds_write_b128 v38, v[24:27] offset:49152
	s_waitcnt vmcnt(24)
	ds_write_b128 v38, v[28:31] offset:57344
	v_lshl_add_u32 v0, s16, 8, v46
	v_ashrrev_i32_e32 v1, 31, v0
	v_lshlrev_b64 v[38:39], 11, v[0:1]
	v_mov_b32_e32 v0, 0
	v_lshl_add_u64 v[40:41], v[34:35], 0, v[38:39]
	v_mov_b32_e32 v1, v0
	v_mov_b32_e32 v2, v0
	v_mov_b32_e32 v3, v0
	v_mov_b32_e32 v4, v0
	v_mov_b32_e32 v5, v0
	v_mov_b32_e32 v6, v0
	v_mov_b32_e32 v7, v0
	v_mov_b32_e32 v8, v0
	v_mov_b32_e32 v9, v0
	v_mov_b32_e32 v10, v0
	v_mov_b32_e32 v11, v0
	v_mov_b32_e32 v12, v0
	v_mov_b32_e32 v13, v0
	v_mov_b32_e32 v14, v0
	v_mov_b32_e32 v15, v0
	v_mov_b32_e32 v16, v0
	v_mov_b32_e32 v17, v0
	v_mov_b32_e32 v18, v0
	v_mov_b32_e32 v19, v0
	v_mov_b32_e32 v20, v0
	v_mov_b32_e32 v21, v0
	v_mov_b32_e32 v22, v0
	v_mov_b32_e32 v23, v0
	v_mov_b32_e32 v24, v0
	v_mov_b32_e32 v25, v0
	v_mov_b32_e32 v26, v0
	v_mov_b32_e32 v27, v0
	v_mov_b32_e32 v28, v0
	v_mov_b32_e32 v29, v0
	v_mov_b32_e32 v30, v0
	v_mov_b32_e32 v31, v0
	s_waitcnt lgkmcnt(0)
	s_barrier
; #define LAS __attribute__((address_space(3)))
; __device__ __forceinline__ void ssm_a_task(unsigned char* ws, LAS unsigned char* lds, int task, int tid) {
;     ...
; #pragma unroll 4
;         for (int ks = 0; ks < 16; ++ks) {
;             bf16x8 bfr[4], afr[2];
; #pragma unroll
;             for (int a = 0; a < 2; ++a) afr[a] = *(const bf16x8*)(WA + (size_t)a * 16 * 1024 + (hh * 16 + ks) * 32);
; #pragma unroll
;             for (int c = 0; c < 4; ++c) bfr[c] = *(const LAS bf16x8*)(lds + SS_UB + (((2 * ks + (kk >> 1)) * 64 + c * 16 + rr) * 32 + (kk & 1) * 16));
; #pragma unroll
;             for (int a = 0; a < 2; ++a)
; #pragma unroll
;                 for (int c = 0; c < 4; ++c) acc[a][c] = __builtin_amdgcn_mfma_f32_16x16x32_bf16(afr[a], bfr[c], acc[a][c], 0, 0, 0);
;         }
.LBB0_604:
	v_add_u32_e32 v166, 0x10000, v47
	ds_read_b128 v[132:135], v166 offset:0
	ds_read_b128 v[136:139], v166 offset:512
	ds_read_b128 v[140:143], v166 offset:1024
	ds_read_b128 v[144:147], v166 offset:1536
	ds_read_b128 v[148:151], v166 offset:4096
	ds_read_b128 v[152:155], v166 offset:4608
	ds_read_b128 v[156:159], v166 offset:5120
	ds_read_b128 v[160:163], v166 offset:5632
	s_waitcnt lgkmcnt(4)
	s_waitcnt vmcnt(23)
	v_mfma_f32_16x16x32_bf16 v[12:15], v[80:83], v[132:135], v[12:15]
	v_mfma_f32_16x16x32_bf16 v[8:11], v[80:83], v[136:139], v[8:11]
	v_mfma_f32_16x16x32_bf16 v[4:7], v[80:83], v[140:143], v[4:7]
	v_mfma_f32_16x16x32_bf16 v[0:3], v[80:83], v[144:147], v[0:3]
	s_waitcnt vmcnt(22)
	v_mfma_f32_16x16x32_bf16 v[28:31], v[84:87], v[132:135], v[28:31]
	v_mfma_f32_16x16x32_bf16 v[24:27], v[84:87], v[136:139], v[24:27]
	v_mfma_f32_16x16x32_bf16 v[20:23], v[84:87], v[140:143], v[20:23]
	v_mfma_f32_16x16x32_bf16 v[16:19], v[84:87], v[144:147], v[16:19]
	global_load_dwordx4 v[80:83], v[40:41], off offset:576
	global_load_dwordx4 v[84:87], v[164:165], off offset:576
	ds_read_b128 v[132:135], v166 offset:8192
	ds_read_b128 v[136:139], v166 offset:8704
	ds_read_b128 v[140:143], v166 offset:9216
	ds_read_b128 v[144:147], v166 offset:9728
	s_waitcnt lgkmcnt(4)
	s_waitcnt vmcnt(23)
	v_mfma_f32_16x16x32_bf16 v[12:15], v[88:91], v[148:151], v[12:15]
	v_mfma_f32_16x16x32_bf16 v[8:11], v[88:91], v[152:155], v[8:11]
	v_mfma_f32_16x16x32_bf16 v[4:7], v[88:91], v[156:159], v[4:7]
	v_mfma_f32_16x16x32_bf16 v[0:3], v[88:91], v[160:163], v[0:3]
	s_waitcnt vmcnt(22)
	v_mfma_f32_16x16x32_bf16 v[28:31], v[92:95], v[148:151], v[28:31]
	v_mfma_f32_16x16x32_bf16 v[24:27], v[92:95], v[152:155], v[24:27]
	v_mfma_f32_16x16x32_bf16 v[20:23], v[92:95], v[156:159], v[20:23]
	v_mfma_f32_16x16x32_bf16 v[16:19], v[92:95], v[160:163], v[16:19]
	global_load_dwordx4 v[88:91], v[40:41], off offset:640
	global_load_dwordx4 v[92:95], v[164:165], off offset:640
	ds_read_b128 v[148:151], v166 offset:12288
	ds_read_b128 v[152:155], v166 offset:12800
	ds_read_b128 v[156:159], v166 offset:13312
	ds_read_b128 v[160:163], v166 offset:13824
	s_waitcnt lgkmcnt(4)
	s_waitcnt vmcnt(23)
	v_mfma_f32_16x16x32_bf16 v[12:15], v[96:99], v[132:135], v[12:15]
	v_mfma_f32_16x16x32_bf16 v[8:11], v[96:99], v[136:139], v[8:11]
	v_mfma_f32_16x16x32_bf16 v[4:7], v[96:99], v[140:143], v[4:7]
	v_mfma_f32_16x16x32_bf16 v[0:3], v[96:99], v[144:147], v[0:3]
	s_waitcnt vmcnt(22)
	v_mfma_f32_16x16x32_bf16 v[28:31], v[100:103], v[132:135], v[28:31]
	v_mfma_f32_16x16x32_bf16 v[24:27], v[100:103], v[136:139], v[24:27]
	v_mfma_f32_16x16x32_bf16 v[20:23], v[100:103], v[140:143], v[20:23]
	v_mfma_f32_16x16x32_bf16 v[16:19], v[100:103], v[144:147], v[16:19]
	global_load_dwordx4 v[96:99], v[40:41], off offset:704
	global_load_dwordx4 v[100:103], v[164:165], off offset:704
	ds_read_b128 v[132:135], v166 offset:16384
	ds_read_b128 v[136:139], v166 offset:16896
	ds_read_b128 v[140:143], v166 offset:17408
	ds_read_b128 v[144:147], v166 offset:17920
	s_waitcnt lgkmcnt(4)
	s_waitcnt vmcnt(23)
	v_mfma_f32_16x16x32_bf16 v[12:15], v[104:107], v[148:151], v[12:15]
	v_mfma_f32_16x16x32_bf16 v[8:11], v[104:107], v[152:155], v[8:11]
	v_mfma_f32_16x16x32_bf16 v[4:7], v[104:107], v[156:159], v[4:7]
	v_mfma_f32_16x16x32_bf16 v[0:3], v[104:107], v[160:163], v[0:3]
	s_waitcnt vmcnt(22)
	v_mfma_f32_16x16x32_bf16 v[28:31], v[108:111], v[148:151], v[28:31]
	v_mfma_f32_16x16x32_bf16 v[24:27], v[108:111], v[152:155], v[24:27]
	v_mfma_f32_16x16x32_bf16 v[20:23], v[108:111], v[156:159], v[20:23]
	v_mfma_f32_16x16x32_bf16 v[16:19], v[108:111], v[160:163], v[16:19]
	global_load_dwordx4 v[104:107], v[40:41], off offset:768
	global_load_dwordx4 v[108:111], v[164:165], off offset:768
	ds_read_b128 v[148:151], v166 offset:20480
	ds_read_b128 v[152:155], v166 offset:20992
	ds_read_b128 v[156:159], v166 offset:21504
	ds_read_b128 v[160:163], v166 offset:22016
	s_waitcnt lgkmcnt(4)
	s_waitcnt vmcnt(23)
	v_mfma_f32_16x16x32_bf16 v[12:15], v[112:115], v[132:135], v[12:15]
	v_mfma_f32_16x16x32_bf16 v[8:11], v[112:115], v[136:139], v[8:11]
	v_mfma_f32_16x16x32_bf16 v[4:7], v[112:115], v[140:143], v[4:7]
	v_mfma_f32_16x16x32_bf16 v[0:3], v[112:115], v[144:147], v[0:3]
	s_waitcnt vmcnt(22)
	v_mfma_f32_16x16x32_bf16 v[28:31], v[116:119], v[132:135], v[28:31]
	v_mfma_f32_16x16x32_bf16 v[24:27], v[116:119], v[136:139], v[24:27]
	v_mfma_f32_16x16x32_bf16 v[20:23], v[116:119], v[140:143], v[20:23]
	v_mfma_f32_16x16x32_bf16 v[16:19], v[116:119], v[144:147], v[16:19]
	ds_read_b128 v[132:135], v166 offset:24576
	ds_read_b128 v[136:139], v166 offset:25088
	ds_read_b128 v[140:143], v166 offset:25600
	ds_read_b128 v[144:147], v166 offset:26112
	s_waitcnt lgkmcnt(4)
	s_waitcnt vmcnt(21)
	v_mfma_f32_16x16x32_bf16 v[12:15], v[120:123], v[148:151], v[12:15]
	v_mfma_f32_16x16x32_bf16 v[8:11], v[120:123], v[152:155], v[8:11]
	v_mfma_f32_16x16x32_bf16 v[4:7], v[120:123], v[156:159], v[4:7]
	v_mfma_f32_16x16x32_bf16 v[0:3], v[120:123], v[160:163], v[0:3]
	s_waitcnt vmcnt(20)
	v_mfma_f32_16x16x32_bf16 v[28:31], v[124:127], v[148:151], v[28:31]
	v_mfma_f32_16x16x32_bf16 v[24:27], v[124:127], v[152:155], v[24:27]
	v_mfma_f32_16x16x32_bf16 v[20:23], v[124:127], v[156:159], v[20:23]
	v_mfma_f32_16x16x32_bf16 v[16:19], v[124:127], v[160:163], v[16:19]
	ds_read_b128 v[148:151], v166 offset:28672
	ds_read_b128 v[152:155], v166 offset:29184
	ds_read_b128 v[156:159], v166 offset:29696
	ds_read_b128 v[160:163], v166 offset:30208
	s_waitcnt lgkmcnt(4)
	s_waitcnt vmcnt(19)
; #define LAS __attribute__((address_space(3)))
; __device__ __forceinline__ void ssm_a_task(unsigned char* ws, LAS unsigned char* lds, int task, int tid) {
;     ...
; #pragma unroll 4
;         for (int ks = 0; ks < 16; ++ks) {
;             bf16x8 bfr[4], afr[2];
; #pragma unroll
;             for (int a = 0; a < 2; ++a) afr[a] = *(const bf16x8*)(WA + (size_t)a * 16 * 1024 + (hh * 16 + ks) * 32);
; #pragma unroll
;             for (int c = 0; c < 4; ++c) bfr[c] = *(const LAS bf16x8*)(lds + SS_UB + (((2 * ks + (kk >> 1)) * 64 + c * 16 + rr) * 32 + (kk & 1) * 16));
; #pragma unroll
;             for (int a = 0; a < 2; ++a)
; #pragma unroll
;                 for (int c = 0; c < 4; ++c) acc[a][c] = __builtin_amdgcn_mfma_f32_16x16x32_bf16(afr[a], bfr[c], acc[a][c], 0, 0, 0);
;         }
	v_mfma_f32_16x16x32_bf16 v[12:15], v[128:131], v[132:135], v[12:15]
	v_mfma_f32_16x16x32_bf16 v[8:11], v[128:131], v[136:139], v[8:11]
	v_mfma_f32_16x16x32_bf16 v[4:7], v[128:131], v[140:143], v[4:7]
	v_mfma_f32_16x16x32_bf16 v[0:3], v[128:131], v[144:147], v[0:3]
	s_waitcnt vmcnt(18)
	v_mfma_f32_16x16x32_bf16 v[28:31], v[168:171], v[132:135], v[28:31]
	v_mfma_f32_16x16x32_bf16 v[24:27], v[168:171], v[136:139], v[24:27]
	v_mfma_f32_16x16x32_bf16 v[20:23], v[168:171], v[140:143], v[20:23]
	v_mfma_f32_16x16x32_bf16 v[16:19], v[168:171], v[144:147], v[16:19]
	ds_read_b128 v[132:135], v166 offset:32768
	ds_read_b128 v[136:139], v166 offset:33280
	ds_read_b128 v[140:143], v166 offset:33792
	ds_read_b128 v[144:147], v166 offset:34304
	s_waitcnt lgkmcnt(4)
	s_waitcnt vmcnt(17)
	v_mfma_f32_16x16x32_bf16 v[12:15], v[172:175], v[148:151], v[12:15]
	v_mfma_f32_16x16x32_bf16 v[8:11], v[172:175], v[152:155], v[8:11]
	v_mfma_f32_16x16x32_bf16 v[4:7], v[172:175], v[156:159], v[4:7]
	v_mfma_f32_16x16x32_bf16 v[0:3], v[172:175], v[160:163], v[0:3]
	s_waitcnt vmcnt(16)
	v_mfma_f32_16x16x32_bf16 v[28:31], v[176:179], v[148:151], v[28:31]
	v_mfma_f32_16x16x32_bf16 v[24:27], v[176:179], v[152:155], v[24:27]
	v_mfma_f32_16x16x32_bf16 v[20:23], v[176:179], v[156:159], v[20:23]
	v_mfma_f32_16x16x32_bf16 v[16:19], v[176:179], v[160:163], v[16:19]
	ds_read_b128 v[148:151], v166 offset:36864
	ds_read_b128 v[152:155], v166 offset:37376
	ds_read_b128 v[156:159], v166 offset:37888
	ds_read_b128 v[160:163], v166 offset:38400
	s_waitcnt lgkmcnt(4)
	s_waitcnt vmcnt(15)
	v_mfma_f32_16x16x32_bf16 v[12:15], v[180:183], v[132:135], v[12:15]
	v_mfma_f32_16x16x32_bf16 v[8:11], v[180:183], v[136:139], v[8:11]
	v_mfma_f32_16x16x32_bf16 v[4:7], v[180:183], v[140:143], v[4:7]
	v_mfma_f32_16x16x32_bf16 v[0:3], v[180:183], v[144:147], v[0:3]
	s_waitcnt vmcnt(14)
	v_mfma_f32_16x16x32_bf16 v[28:31], v[186:189], v[132:135], v[28:31]
	v_mfma_f32_16x16x32_bf16 v[24:27], v[186:189], v[136:139], v[24:27]
	v_mfma_f32_16x16x32_bf16 v[20:23], v[186:189], v[140:143], v[20:23]
	v_mfma_f32_16x16x32_bf16 v[16:19], v[186:189], v[144:147], v[16:19]
	ds_read_b128 v[132:135], v166 offset:40960
	ds_read_b128 v[136:139], v166 offset:41472
	ds_read_b128 v[140:143], v166 offset:41984
	ds_read_b128 v[144:147], v166 offset:42496
	s_waitcnt lgkmcnt(4)
	s_waitcnt vmcnt(13)
	v_mfma_f32_16x16x32_bf16 v[12:15], v[190:193], v[148:151], v[12:15]
	v_mfma_f32_16x16x32_bf16 v[8:11], v[190:193], v[152:155], v[8:11]
	v_mfma_f32_16x16x32_bf16 v[4:7], v[190:193], v[156:159], v[4:7]
	v_mfma_f32_16x16x32_bf16 v[0:3], v[190:193], v[160:163], v[0:3]
	s_waitcnt vmcnt(12)
	v_mfma_f32_16x16x32_bf16 v[28:31], v[194:197], v[148:151], v[28:31]
	v_mfma_f32_16x16x32_bf16 v[24:27], v[194:197], v[152:155], v[24:27]
	v_mfma_f32_16x16x32_bf16 v[20:23], v[194:197], v[156:159], v[20:23]
	v_mfma_f32_16x16x32_bf16 v[16:19], v[194:197], v[160:163], v[16:19]
	ds_read_b128 v[148:151], v166 offset:45056
	ds_read_b128 v[152:155], v166 offset:45568
	ds_read_b128 v[156:159], v166 offset:46080
	ds_read_b128 v[160:163], v166 offset:46592
	s_waitcnt lgkmcnt(4)
	s_waitcnt vmcnt(11)
	v_mfma_f32_16x16x32_bf16 v[12:15], v[198:201], v[132:135], v[12:15]
	v_mfma_f32_16x16x32_bf16 v[8:11], v[198:201], v[136:139], v[8:11]
	v_mfma_f32_16x16x32_bf16 v[4:7], v[198:201], v[140:143], v[4:7]
	v_mfma_f32_16x16x32_bf16 v[0:3], v[198:201], v[144:147], v[0:3]
	s_waitcnt vmcnt(10)
	v_mfma_f32_16x16x32_bf16 v[28:31], v[202:205], v[132:135], v[28:31]
	v_mfma_f32_16x16x32_bf16 v[24:27], v[202:205], v[136:139], v[24:27]
	v_mfma_f32_16x16x32_bf16 v[20:23], v[202:205], v[140:143], v[20:23]
	v_mfma_f32_16x16x32_bf16 v[16:19], v[202:205], v[144:147], v[16:19]
	ds_read_b128 v[132:135], v166 offset:49152
	ds_read_b128 v[136:139], v166 offset:49664
	ds_read_b128 v[140:143], v166 offset:50176
	ds_read_b128 v[144:147], v166 offset:50688
	s_waitcnt lgkmcnt(4)
	s_waitcnt vmcnt(9)
	v_mfma_f32_16x16x32_bf16 v[12:15], v[206:209], v[148:151], v[12:15]
	v_mfma_f32_16x16x32_bf16 v[8:11], v[206:209], v[152:155], v[8:11]
	v_mfma_f32_16x16x32_bf16 v[4:7], v[206:209], v[156:159], v[4:7]
	v_mfma_f32_16x16x32_bf16 v[0:3], v[206:209], v[160:163], v[0:3]
	s_waitcnt vmcnt(8)
	v_mfma_f32_16x16x32_bf16 v[28:31], v[210:213], v[148:151], v[28:31]
	v_mfma_f32_16x16x32_bf16 v[24:27], v[210:213], v[152:155], v[24:27]
	v_mfma_f32_16x16x32_bf16 v[20:23], v[210:213], v[156:159], v[20:23]
	v_mfma_f32_16x16x32_bf16 v[16:19], v[210:213], v[160:163], v[16:19]
	ds_read_b128 v[148:151], v166 offset:53248
	ds_read_b128 v[152:155], v166 offset:53760
	ds_read_b128 v[156:159], v166 offset:54272
	ds_read_b128 v[160:163], v166 offset:54784
	s_waitcnt lgkmcnt(4)
	s_waitcnt vmcnt(7)
	v_mfma_f32_16x16x32_bf16 v[12:15], v[80:83], v[132:135], v[12:15]
	v_mfma_f32_16x16x32_bf16 v[8:11], v[80:83], v[136:139], v[8:11]
	v_mfma_f32_16x16x32_bf16 v[4:7], v[80:83], v[140:143], v[4:7]
	v_mfma_f32_16x16x32_bf16 v[0:3], v[80:83], v[144:147], v[0:3]
	s_waitcnt vmcnt(6)
	v_mfma_f32_16x16x32_bf16 v[28:31], v[84:87], v[132:135], v[28:31]
	v_mfma_f32_16x16x32_bf16 v[24:27], v[84:87], v[136:139], v[24:27]
	v_mfma_f32_16x16x32_bf16 v[20:23], v[84:87], v[140:143], v[20:23]
	v_mfma_f32_16x16x32_bf16 v[16:19], v[84:87], v[144:147], v[16:19]
	ds_read_b128 v[132:135], v166 offset:57344
	ds_read_b128 v[136:139], v166 offset:57856
	ds_read_b128 v[140:143], v166 offset:58368
	ds_read_b128 v[144:147], v166 offset:58880
	s_waitcnt lgkmcnt(4)
	s_waitcnt vmcnt(5)
	v_mfma_f32_16x16x32_bf16 v[12:15], v[88:91], v[148:151], v[12:15]
	v_mfma_f32_16x16x32_bf16 v[8:11], v[88:91], v[152:155], v[8:11]
	v_mfma_f32_16x16x32_bf16 v[4:7], v[88:91], v[156:159], v[4:7]
	v_mfma_f32_16x16x32_bf16 v[0:3], v[88:91], v[160:163], v[0:3]
	s_waitcnt vmcnt(4)
; #define LAS __attribute__((address_space(3)))
; __device__ __forceinline__ void ssm_stage_u(unsigned char* ws, LAS unsigned char* lds, int g, int cb, int hh, int tid) {
;     asm volatile("" : "+v"(tid));
;     const bf16* U = (const bf16*)(ws + AR_U);
;     u32x4 v[8];
; #pragma unroll
;     for (int r = 0; r < 8; ++r) { const int c = r * 512 + tid, jj = c >> 7, col = (c >> 1) & 63, part = c & 1;
;         v[r] = *(const u32x4*)(U + ((size_t)((cb * 64 + col) * 64 + hh * 32 + jj) * 512 + g * 16 + part * 8)); }
; #pragma unroll
;     for (int r = 0; r < 8; ++r) { const int c = r * 512 + tid; *(LAS u32x4*)(lds + SS_UB + c * 16) = v[r]; }
; }
; __device__ __forceinline__ void ssm_a_task(unsigned char* ws, LAS unsigned char* lds, int task, int tid) {
;     ...
;     for (int hh = 0; hh < 2; ++hh) {
;         ssm_stage_u(ws, lds, g, cb, hh, tid);
;         __syncthreads();
; #pragma unroll 4
;         for (int ks = 0; ks < 16; ++ks) {
;             bf16x8 bfr[4], afr[2];
; #pragma unroll
;             for (int a = 0; a < 2; ++a) afr[a] = *(const bf16x8*)(WA + (size_t)a * 16 * 1024 + (hh * 16 + ks) * 32);
; #pragma unroll
;             for (int c = 0; c < 4; ++c) bfr[c] = *(const LAS bf16x8*)(lds + SS_UB + (((2 * ks + (kk >> 1)) * 64 + c * 16 + rr) * 32 + (kk & 1) * 16));
; #pragma unroll
;             for (int a = 0; a < 2; ++a)
; #pragma unroll
;                 for (int c = 0; c < 4; ++c) acc[a][c] = __builtin_amdgcn_mfma_f32_16x16x32_bf16(afr[a], bfr[c], acc[a][c], 0, 0, 0);
;         }
;         __syncthreads();
	v_mfma_f32_16x16x32_bf16 v[28:31], v[92:95], v[148:151], v[28:31]
	v_mfma_f32_16x16x32_bf16 v[24:27], v[92:95], v[152:155], v[24:27]
	v_mfma_f32_16x16x32_bf16 v[20:23], v[92:95], v[156:159], v[20:23]
	v_mfma_f32_16x16x32_bf16 v[16:19], v[92:95], v[160:163], v[16:19]
	ds_read_b128 v[148:151], v166 offset:61440
	ds_read_b128 v[152:155], v166 offset:61952
	ds_read_b128 v[156:159], v166 offset:62464
	ds_read_b128 v[160:163], v166 offset:62976
	s_waitcnt lgkmcnt(4)
	s_waitcnt vmcnt(3)
	v_mfma_f32_16x16x32_bf16 v[12:15], v[96:99], v[132:135], v[12:15]
	v_mfma_f32_16x16x32_bf16 v[8:11], v[96:99], v[136:139], v[8:11]
	v_mfma_f32_16x16x32_bf16 v[4:7], v[96:99], v[140:143], v[4:7]
	v_mfma_f32_16x16x32_bf16 v[0:3], v[96:99], v[144:147], v[0:3]
	s_waitcnt vmcnt(2)
	v_mfma_f32_16x16x32_bf16 v[28:31], v[100:103], v[132:135], v[28:31]
	v_mfma_f32_16x16x32_bf16 v[24:27], v[100:103], v[136:139], v[24:27]
	v_mfma_f32_16x16x32_bf16 v[20:23], v[100:103], v[140:143], v[20:23]
	v_mfma_f32_16x16x32_bf16 v[16:19], v[100:103], v[144:147], v[16:19]
	s_waitcnt lgkmcnt(0)
	s_waitcnt vmcnt(1)
	v_mfma_f32_16x16x32_bf16 v[12:15], v[104:107], v[148:151], v[12:15]
	v_mfma_f32_16x16x32_bf16 v[8:11], v[104:107], v[152:155], v[8:11]
	v_mfma_f32_16x16x32_bf16 v[4:7], v[104:107], v[156:159], v[4:7]
	v_mfma_f32_16x16x32_bf16 v[0:3], v[104:107], v[160:163], v[0:3]
	s_waitcnt vmcnt(0)
	v_mfma_f32_16x16x32_bf16 v[28:31], v[108:111], v[148:151], v[28:31]
	v_mfma_f32_16x16x32_bf16 v[24:27], v[108:111], v[152:155], v[24:27]
	v_mfma_f32_16x16x32_bf16 v[20:23], v[108:111], v[156:159], v[20:23]
	v_mfma_f32_16x16x32_bf16 v[16:19], v[108:111], v[160:163], v[16:19]
	s_mov_b32 s12, 0x10000
	v_mov_b32_e32 v72, v44
	s_barrier
	v_lshl_add_u64 v[38:39], v[36:37], 0, v[38:39]
	v_lshlrev_b32_e32 v40, 5, v72
	v_and_b32_e32 v40, 0xfc0, v40
	v_or3_b32 v73, s3, v40, 32
	v_lshlrev_b32_e32 v76, 4, v72
	v_ashrrev_i32_e32 v40, 7, v72
	v_add_u32_e32 v42, 0x200, v72
	v_add_u32_e32 v52, 0x400, v72
	v_add_u32_e32 v54, 0x600, v72
	v_add_u32_e32 v60, 0x800, v72
	v_add_u32_e32 v62, 0xa00, v72
	v_add_u32_e32 v70, 0xc00, v72
	v_add_u32_e32 v72, 0xe00, v72
	v_ashrrev_i32_e32 v42, 7, v42
	v_ashrrev_i32_e32 v52, 7, v52
	v_ashrrev_i32_e32 v54, 7, v54
	v_ashrrev_i32_e32 v60, 7, v60
	v_ashrrev_i32_e32 v62, 7, v62
	v_ashrrev_i32_e32 v70, 7, v70
	v_ashrrev_i32_e32 v72, 7, v72
	v_add_u32_e32 v40, v73, v40
	v_add_u32_e32 v42, v73, v42
	v_add_u32_e32 v52, v73, v52
	v_add_u32_e32 v54, v73, v54
	v_add_u32_e32 v60, v73, v60
	v_add_u32_e32 v62, v73, v62
	v_add_u32_e32 v70, v73, v70
	v_add_u32_e32 v72, v73, v72
	v_and_b32_e32 v184, 16, v76
	v_ashrrev_i32_e32 v41, 31, v40
	v_ashrrev_i32_e32 v43, 31, v42
	v_ashrrev_i32_e32 v53, 31, v52
	v_ashrrev_i32_e32 v55, 31, v54
	v_ashrrev_i32_e32 v61, 31, v60
	v_ashrrev_i32_e32 v63, 31, v62
	v_ashrrev_i32_e32 v71, 31, v70
	v_ashrrev_i32_e32 v73, 31, v72
	v_lshl_add_u64 v[68:69], s[34:35], 0, v[184:185]
	v_lshlrev_b64 v[40:41], 10, v[40:41]
	v_lshlrev_b64 v[42:43], 10, v[42:43]
	v_lshlrev_b64 v[52:53], 10, v[52:53]
	v_lshlrev_b64 v[54:55], 10, v[54:55]
	v_lshlrev_b64 v[60:61], 10, v[60:61]
	v_lshlrev_b64 v[62:63], 10, v[62:63]
	v_lshlrev_b64 v[70:71], 10, v[70:71]
	v_lshlrev_b64 v[72:73], 10, v[72:73]
	v_lshl_add_u64 v[40:41], v[68:69], 0, v[40:41]
	v_lshl_add_u64 v[48:49], v[68:69], 0, v[42:43]
	v_lshl_add_u64 v[52:53], v[68:69], 0, v[52:53]
	v_lshl_add_u64 v[56:57], v[68:69], 0, v[54:55]
	v_lshl_add_u64 v[60:61], v[68:69], 0, v[60:61]
	v_lshl_add_u64 v[64:65], v[68:69], 0, v[62:63]
	v_lshl_add_u64 v[70:71], v[68:69], 0, v[70:71]
	v_lshl_add_u64 v[72:73], v[68:69], 0, v[72:73]
	global_load_dwordx4 v[40:43], v[40:41], off
	s_nop 0
	global_load_dwordx4 v[48:51], v[48:49], off
	s_nop 0
	global_load_dwordx4 v[52:55], v[52:53], off
	s_nop 0
	global_load_dwordx4 v[56:59], v[56:57], off
	s_nop 0
	global_load_dwordx4 v[60:63], v[60:61], off
	s_nop 0
	global_load_dwordx4 v[64:67], v[64:65], off
	s_nop 0
	global_load_dwordx4 v[68:71], v[70:71], off
	s_nop 0
	global_load_dwordx4 v[72:75], v[72:73], off
	v_add_u32_e32 v76, 0, v76
	v_add_u32_e32 v76, 0x10000, v76
	s_mov_b32 s3, 0
	v_add_co_u32_e32 v164, vcc, 0xffff8000, v38
	s_nop 1
	v_addc_co_u32_e32 v165, vcc, -1, v39, vcc
	global_load_dwordx4 v[80:83], v[38:39], off offset:-192
	global_load_dwordx4 v[84:87], v[164:165], off offset:-192
	global_load_dwordx4 v[88:91], v[38:39], off offset:-128
	global_load_dwordx4 v[92:95], v[164:165], off offset:-128
	global_load_dwordx4 v[96:99], v[38:39], off offset:-64
	global_load_dwordx4 v[100:103], v[164:165], off offset:-64
	global_load_dwordx4 v[104:107], v[38:39], off offset:0
	global_load_dwordx4 v[108:111], v[164:165], off offset:0
	global_load_dwordx4 v[112:115], v[38:39], off offset:64
	global_load_dwordx4 v[116:119], v[164:165], off offset:64
	global_load_dwordx4 v[120:123], v[38:39], off offset:128
	global_load_dwordx4 v[124:127], v[164:165], off offset:128
	global_load_dwordx4 v[128:131], v[38:39], off offset:192
	global_load_dwordx4 v[168:171], v[164:165], off offset:192
	global_load_dwordx4 v[172:175], v[38:39], off offset:256
	global_load_dwordx4 v[176:179], v[164:165], off offset:256
	global_load_dwordx4 v[180:183], v[38:39], off offset:320
	global_load_dwordx4 v[186:189], v[164:165], off offset:320
	global_load_dwordx4 v[190:193], v[38:39], off offset:384
	global_load_dwordx4 v[194:197], v[164:165], off offset:384
	global_load_dwordx4 v[198:201], v[38:39], off offset:448
	global_load_dwordx4 v[202:205], v[164:165], off offset:448
	global_load_dwordx4 v[206:209], v[38:39], off offset:512
	global_load_dwordx4 v[210:213], v[164:165], off offset:512
	s_waitcnt vmcnt(31)
	ds_write_b128 v76, v[40:43]
	s_waitcnt vmcnt(30)
	ds_write_b128 v76, v[48:51] offset:8192
	s_waitcnt vmcnt(29)
	ds_write_b128 v76, v[52:55] offset:16384
	s_waitcnt vmcnt(28)
	ds_write_b128 v76, v[56:59] offset:24576
	s_waitcnt vmcnt(27)
	ds_write_b128 v76, v[60:63] offset:32768
	s_waitcnt vmcnt(26)
	ds_write_b128 v76, v[64:67] offset:40960
	s_waitcnt vmcnt(25)
	ds_write_b128 v76, v[68:71] offset:49152
	s_waitcnt vmcnt(24)
	ds_write_b128 v76, v[72:75] offset:57344
	s_waitcnt lgkmcnt(0)
	s_barrier
; #define LAS __attribute__((address_space(3)))
; __device__ __forceinline__ void ssm_a_task(unsigned char* ws, LAS unsigned char* lds, int task, int tid) {
;     ...
; #pragma unroll 4
;         for (int ks = 0; ks < 16; ++ks) {
;             bf16x8 bfr[4], afr[2];
; #pragma unroll
;             for (int a = 0; a < 2; ++a) afr[a] = *(const bf16x8*)(WA + (size_t)a * 16 * 1024 + (hh * 16 + ks) * 32);
; #pragma unroll
;             for (int c = 0; c < 4; ++c) bfr[c] = *(const LAS bf16x8*)(lds + SS_UB + (((2 * ks + (kk >> 1)) * 64 + c * 16 + rr) * 32 + (kk & 1) * 16));
; #pragma unroll
;             for (int a = 0; a < 2; ++a)
; #pragma unroll
;                 for (int c = 0; c < 4; ++c) acc[a][c] = __builtin_amdgcn_mfma_f32_16x16x32_bf16(afr[a], bfr[c], acc[a][c], 0, 0, 0);
;         }
.LBB0_606:
	v_add_u32_e32 v166, 0x10000, v47
	ds_read_b128 v[132:135], v166 offset:0
	ds_read_b128 v[136:139], v166 offset:512
	ds_read_b128 v[140:143], v166 offset:1024
	ds_read_b128 v[144:147], v166 offset:1536
	ds_read_b128 v[148:151], v166 offset:4096
	ds_read_b128 v[152:155], v166 offset:4608
	ds_read_b128 v[156:159], v166 offset:5120
	ds_read_b128 v[160:163], v166 offset:5632
	s_waitcnt lgkmcnt(4)
	s_waitcnt vmcnt(23)
	v_mfma_f32_16x16x32_bf16 v[12:15], v[80:83], v[132:135], v[12:15]
	v_mfma_f32_16x16x32_bf16 v[8:11], v[80:83], v[136:139], v[8:11]
	v_mfma_f32_16x16x32_bf16 v[4:7], v[80:83], v[140:143], v[4:7]
	v_mfma_f32_16x16x32_bf16 v[0:3], v[80:83], v[144:147], v[0:3]
	s_waitcnt vmcnt(22)
	v_mfma_f32_16x16x32_bf16 v[28:31], v[84:87], v[132:135], v[28:31]
	v_mfma_f32_16x16x32_bf16 v[24:27], v[84:87], v[136:139], v[24:27]
	v_mfma_f32_16x16x32_bf16 v[20:23], v[84:87], v[140:143], v[20:23]
	v_mfma_f32_16x16x32_bf16 v[16:19], v[84:87], v[144:147], v[16:19]
	global_load_dwordx4 v[80:83], v[38:39], off offset:576
	global_load_dwordx4 v[84:87], v[164:165], off offset:576
	ds_read_b128 v[132:135], v166 offset:8192
	ds_read_b128 v[136:139], v166 offset:8704
	ds_read_b128 v[140:143], v166 offset:9216
	ds_read_b128 v[144:147], v166 offset:9728
	s_waitcnt lgkmcnt(4)
	s_waitcnt vmcnt(23)
	v_mfma_f32_16x16x32_bf16 v[12:15], v[88:91], v[148:151], v[12:15]
	v_mfma_f32_16x16x32_bf16 v[8:11], v[88:91], v[152:155], v[8:11]
	v_mfma_f32_16x16x32_bf16 v[4:7], v[88:91], v[156:159], v[4:7]
	v_mfma_f32_16x16x32_bf16 v[0:3], v[88:91], v[160:163], v[0:3]
	s_waitcnt vmcnt(22)
	v_mfma_f32_16x16x32_bf16 v[28:31], v[92:95], v[148:151], v[28:31]
	v_mfma_f32_16x16x32_bf16 v[24:27], v[92:95], v[152:155], v[24:27]
	v_mfma_f32_16x16x32_bf16 v[20:23], v[92:95], v[156:159], v[20:23]
	v_mfma_f32_16x16x32_bf16 v[16:19], v[92:95], v[160:163], v[16:19]
	global_load_dwordx4 v[88:91], v[38:39], off offset:640
	global_load_dwordx4 v[92:95], v[164:165], off offset:640
	ds_read_b128 v[148:151], v166 offset:12288
	ds_read_b128 v[152:155], v166 offset:12800
	ds_read_b128 v[156:159], v166 offset:13312
	ds_read_b128 v[160:163], v166 offset:13824
	s_waitcnt lgkmcnt(4)
	s_waitcnt vmcnt(23)
	v_mfma_f32_16x16x32_bf16 v[12:15], v[96:99], v[132:135], v[12:15]
	v_mfma_f32_16x16x32_bf16 v[8:11], v[96:99], v[136:139], v[8:11]
	v_mfma_f32_16x16x32_bf16 v[4:7], v[96:99], v[140:143], v[4:7]
	v_mfma_f32_16x16x32_bf16 v[0:3], v[96:99], v[144:147], v[0:3]
	s_waitcnt vmcnt(22)
	v_mfma_f32_16x16x32_bf16 v[28:31], v[100:103], v[132:135], v[28:31]
	v_mfma_f32_16x16x32_bf16 v[24:27], v[100:103], v[136:139], v[24:27]
	v_mfma_f32_16x16x32_bf16 v[20:23], v[100:103], v[140:143], v[20:23]
	v_mfma_f32_16x16x32_bf16 v[16:19], v[100:103], v[144:147], v[16:19]
	global_load_dwordx4 v[96:99], v[38:39], off offset:704
	global_load_dwordx4 v[100:103], v[164:165], off offset:704
	ds_read_b128 v[132:135], v166 offset:16384
	ds_read_b128 v[136:139], v166 offset:16896
	ds_read_b128 v[140:143], v166 offset:17408
	ds_read_b128 v[144:147], v166 offset:17920
	s_waitcnt lgkmcnt(4)
	s_waitcnt vmcnt(23)
	v_mfma_f32_16x16x32_bf16 v[12:15], v[104:107], v[148:151], v[12:15]
	v_mfma_f32_16x16x32_bf16 v[8:11], v[104:107], v[152:155], v[8:11]
	v_mfma_f32_16x16x32_bf16 v[4:7], v[104:107], v[156:159], v[4:7]
	v_mfma_f32_16x16x32_bf16 v[0:3], v[104:107], v[160:163], v[0:3]
	s_waitcnt vmcnt(22)
	v_mfma_f32_16x16x32_bf16 v[28:31], v[108:111], v[148:151], v[28:31]
	v_mfma_f32_16x16x32_bf16 v[24:27], v[108:111], v[152:155], v[24:27]
	v_mfma_f32_16x16x32_bf16 v[20:23], v[108:111], v[156:159], v[20:23]
	v_mfma_f32_16x16x32_bf16 v[16:19], v[108:111], v[160:163], v[16:19]
	global_load_dwordx4 v[104:107], v[38:39], off offset:768
	global_load_dwordx4 v[108:111], v[164:165], off offset:768
	ds_read_b128 v[148:151], v166 offset:20480
	ds_read_b128 v[152:155], v166 offset:20992
	ds_read_b128 v[156:159], v166 offset:21504
	ds_read_b128 v[160:163], v166 offset:22016
	s_waitcnt lgkmcnt(4)
	s_waitcnt vmcnt(23)
	v_mfma_f32_16x16x32_bf16 v[12:15], v[112:115], v[132:135], v[12:15]
	v_mfma_f32_16x16x32_bf16 v[8:11], v[112:115], v[136:139], v[8:11]
	v_mfma_f32_16x16x32_bf16 v[4:7], v[112:115], v[140:143], v[4:7]
	v_mfma_f32_16x16x32_bf16 v[0:3], v[112:115], v[144:147], v[0:3]
	s_waitcnt vmcnt(22)
	v_mfma_f32_16x16x32_bf16 v[28:31], v[116:119], v[132:135], v[28:31]
	v_mfma_f32_16x16x32_bf16 v[24:27], v[116:119], v[136:139], v[24:27]
	v_mfma_f32_16x16x32_bf16 v[20:23], v[116:119], v[140:143], v[20:23]
	v_mfma_f32_16x16x32_bf16 v[16:19], v[116:119], v[144:147], v[16:19]
	ds_read_b128 v[132:135], v166 offset:24576
	ds_read_b128 v[136:139], v166 offset:25088
	ds_read_b128 v[140:143], v166 offset:25600
	ds_read_b128 v[144:147], v166 offset:26112
	s_waitcnt lgkmcnt(4)
	s_waitcnt vmcnt(21)
	v_mfma_f32_16x16x32_bf16 v[12:15], v[120:123], v[148:151], v[12:15]
	v_mfma_f32_16x16x32_bf16 v[8:11], v[120:123], v[152:155], v[8:11]
	v_mfma_f32_16x16x32_bf16 v[4:7], v[120:123], v[156:159], v[4:7]
	v_mfma_f32_16x16x32_bf16 v[0:3], v[120:123], v[160:163], v[0:3]
	s_waitcnt vmcnt(20)
	v_mfma_f32_16x16x32_bf16 v[28:31], v[124:127], v[148:151], v[28:31]
	v_mfma_f32_16x16x32_bf16 v[24:27], v[124:127], v[152:155], v[24:27]
	v_mfma_f32_16x16x32_bf16 v[20:23], v[124:127], v[156:159], v[20:23]
	v_mfma_f32_16x16x32_bf16 v[16:19], v[124:127], v[160:163], v[16:19]
	ds_read_b128 v[148:151], v166 offset:28672
	ds_read_b128 v[152:155], v166 offset:29184
	ds_read_b128 v[156:159], v166 offset:29696
	ds_read_b128 v[160:163], v166 offset:30208
	s_waitcnt lgkmcnt(4)
	s_waitcnt vmcnt(19)
; #define LAS __attribute__((address_space(3)))
; __device__ __forceinline__ void ssm_a_task(unsigned char* ws, LAS unsigned char* lds, int task, int tid) {
;     ...
; #pragma unroll 4
;         for (int ks = 0; ks < 16; ++ks) {
;             bf16x8 bfr[4], afr[2];
; #pragma unroll
;             for (int a = 0; a < 2; ++a) afr[a] = *(const bf16x8*)(WA + (size_t)a * 16 * 1024 + (hh * 16 + ks) * 32);
; #pragma unroll
;             for (int c = 0; c < 4; ++c) bfr[c] = *(const LAS bf16x8*)(lds + SS_UB + (((2 * ks + (kk >> 1)) * 64 + c * 16 + rr) * 32 + (kk & 1) * 16));
; #pragma unroll
;             for (int a = 0; a < 2; ++a)
; #pragma unroll
;                 for (int c = 0; c < 4; ++c) acc[a][c] = __builtin_amdgcn_mfma_f32_16x16x32_bf16(afr[a], bfr[c], acc[a][c], 0, 0, 0);
;         }
	v_mfma_f32_16x16x32_bf16 v[12:15], v[128:131], v[132:135], v[12:15]
	v_mfma_f32_16x16x32_bf16 v[8:11], v[128:131], v[136:139], v[8:11]
	v_mfma_f32_16x16x32_bf16 v[4:7], v[128:131], v[140:143], v[4:7]
	v_mfma_f32_16x16x32_bf16 v[0:3], v[128:131], v[144:147], v[0:3]
	s_waitcnt vmcnt(18)
	v_mfma_f32_16x16x32_bf16 v[28:31], v[168:171], v[132:135], v[28:31]
	v_mfma_f32_16x16x32_bf16 v[24:27], v[168:171], v[136:139], v[24:27]
	v_mfma_f32_16x16x32_bf16 v[20:23], v[168:171], v[140:143], v[20:23]
	v_mfma_f32_16x16x32_bf16 v[16:19], v[168:171], v[144:147], v[16:19]
	ds_read_b128 v[132:135], v166 offset:32768
	ds_read_b128 v[136:139], v166 offset:33280
	ds_read_b128 v[140:143], v166 offset:33792
	ds_read_b128 v[144:147], v166 offset:34304
	s_waitcnt lgkmcnt(4)
	s_waitcnt vmcnt(17)
	v_mfma_f32_16x16x32_bf16 v[12:15], v[172:175], v[148:151], v[12:15]
	v_mfma_f32_16x16x32_bf16 v[8:11], v[172:175], v[152:155], v[8:11]
	v_mfma_f32_16x16x32_bf16 v[4:7], v[172:175], v[156:159], v[4:7]
	v_mfma_f32_16x16x32_bf16 v[0:3], v[172:175], v[160:163], v[0:3]
	s_waitcnt vmcnt(16)
	v_mfma_f32_16x16x32_bf16 v[28:31], v[176:179], v[148:151], v[28:31]
	v_mfma_f32_16x16x32_bf16 v[24:27], v[176:179], v[152:155], v[24:27]
	v_mfma_f32_16x16x32_bf16 v[20:23], v[176:179], v[156:159], v[20:23]
	v_mfma_f32_16x16x32_bf16 v[16:19], v[176:179], v[160:163], v[16:19]
	ds_read_b128 v[148:151], v166 offset:36864
	ds_read_b128 v[152:155], v166 offset:37376
	ds_read_b128 v[156:159], v166 offset:37888
	ds_read_b128 v[160:163], v166 offset:38400
	s_waitcnt lgkmcnt(4)
	s_waitcnt vmcnt(15)
	v_mfma_f32_16x16x32_bf16 v[12:15], v[180:183], v[132:135], v[12:15]
	v_mfma_f32_16x16x32_bf16 v[8:11], v[180:183], v[136:139], v[8:11]
	v_mfma_f32_16x16x32_bf16 v[4:7], v[180:183], v[140:143], v[4:7]
	v_mfma_f32_16x16x32_bf16 v[0:3], v[180:183], v[144:147], v[0:3]
	s_waitcnt vmcnt(14)
	v_mfma_f32_16x16x32_bf16 v[28:31], v[186:189], v[132:135], v[28:31]
	v_mfma_f32_16x16x32_bf16 v[24:27], v[186:189], v[136:139], v[24:27]
	v_mfma_f32_16x16x32_bf16 v[20:23], v[186:189], v[140:143], v[20:23]
	v_mfma_f32_16x16x32_bf16 v[16:19], v[186:189], v[144:147], v[16:19]
	ds_read_b128 v[132:135], v166 offset:40960
	ds_read_b128 v[136:139], v166 offset:41472
	ds_read_b128 v[140:143], v166 offset:41984
	ds_read_b128 v[144:147], v166 offset:42496
	s_waitcnt lgkmcnt(4)
	s_waitcnt vmcnt(13)
	v_mfma_f32_16x16x32_bf16 v[12:15], v[190:193], v[148:151], v[12:15]
	v_mfma_f32_16x16x32_bf16 v[8:11], v[190:193], v[152:155], v[8:11]
	v_mfma_f32_16x16x32_bf16 v[4:7], v[190:193], v[156:159], v[4:7]
	v_mfma_f32_16x16x32_bf16 v[0:3], v[190:193], v[160:163], v[0:3]
	s_waitcnt vmcnt(12)
	v_mfma_f32_16x16x32_bf16 v[28:31], v[194:197], v[148:151], v[28:31]
	v_mfma_f32_16x16x32_bf16 v[24:27], v[194:197], v[152:155], v[24:27]
	v_mfma_f32_16x16x32_bf16 v[20:23], v[194:197], v[156:159], v[20:23]
	v_mfma_f32_16x16x32_bf16 v[16:19], v[194:197], v[160:163], v[16:19]
	ds_read_b128 v[148:151], v166 offset:45056
	ds_read_b128 v[152:155], v166 offset:45568
	ds_read_b128 v[156:159], v166 offset:46080
	ds_read_b128 v[160:163], v166 offset:46592
	s_waitcnt lgkmcnt(4)
	s_waitcnt vmcnt(11)
	v_mfma_f32_16x16x32_bf16 v[12:15], v[198:201], v[132:135], v[12:15]
	v_mfma_f32_16x16x32_bf16 v[8:11], v[198:201], v[136:139], v[8:11]
	v_mfma_f32_16x16x32_bf16 v[4:7], v[198:201], v[140:143], v[4:7]
	v_mfma_f32_16x16x32_bf16 v[0:3], v[198:201], v[144:147], v[0:3]
	s_waitcnt vmcnt(10)
	v_mfma_f32_16x16x32_bf16 v[28:31], v[202:205], v[132:135], v[28:31]
	v_mfma_f32_16x16x32_bf16 v[24:27], v[202:205], v[136:139], v[24:27]
	v_mfma_f32_16x16x32_bf16 v[20:23], v[202:205], v[140:143], v[20:23]
	v_mfma_f32_16x16x32_bf16 v[16:19], v[202:205], v[144:147], v[16:19]
	ds_read_b128 v[132:135], v166 offset:49152
	ds_read_b128 v[136:139], v166 offset:49664
	ds_read_b128 v[140:143], v166 offset:50176
	ds_read_b128 v[144:147], v166 offset:50688
	s_waitcnt lgkmcnt(4)
	s_waitcnt vmcnt(9)
	v_mfma_f32_16x16x32_bf16 v[12:15], v[206:209], v[148:151], v[12:15]
	v_mfma_f32_16x16x32_bf16 v[8:11], v[206:209], v[152:155], v[8:11]
	v_mfma_f32_16x16x32_bf16 v[4:7], v[206:209], v[156:159], v[4:7]
	v_mfma_f32_16x16x32_bf16 v[0:3], v[206:209], v[160:163], v[0:3]
	s_waitcnt vmcnt(8)
; #define LAS __attribute__((address_space(3)))
; __device__ __forceinline__ void ssm_a_task(unsigned char* ws, LAS unsigned char* lds, int task, int tid) {
;     ...
; #pragma unroll 4
;         for (int ks = 0; ks < 16; ++ks) {
;             bf16x8 bfr[4], afr[2];
; #pragma unroll
;             for (int a = 0; a < 2; ++a) afr[a] = *(const bf16x8*)(WA + (size_t)a * 16 * 1024 + (hh * 16 + ks) * 32);
; #pragma unroll
;             for (int c = 0; c < 4; ++c) bfr[c] = *(const LAS bf16x8*)(lds + SS_UB + (((2 * ks + (kk >> 1)) * 64 + c * 16 + rr) * 32 + (kk & 1) * 16));
; #pragma unroll
;             for (int a = 0; a < 2; ++a)
; #pragma unroll
;                 for (int c = 0; c < 4; ++c) acc[a][c] = __builtin_amdgcn_mfma_f32_16x16x32_bf16(afr[a], bfr[c], acc[a][c], 0, 0, 0);
;         }
;         __syncthreads();
;     }
;     float* S = (float*)(ws + AR_S);
; #pragma unroll
;     for (int a = 0; a < 2; ++a)
; #pragma unroll
;         for (int c = 0; c < 4; ++c) { const int col = cb * 64 + c * 16 + rr; *(f32x4*)(S + ((size_t)(col * NG + g) * 256 + wid * 32 + a * 16 + 4 * kk)) = acc[a][c]; }
	v_mfma_f32_16x16x32_bf16 v[28:31], v[210:213], v[148:151], v[28:31]
	v_mfma_f32_16x16x32_bf16 v[24:27], v[210:213], v[152:155], v[24:27]
	v_mfma_f32_16x16x32_bf16 v[20:23], v[210:213], v[156:159], v[20:23]
	v_mfma_f32_16x16x32_bf16 v[16:19], v[210:213], v[160:163], v[16:19]
	ds_read_b128 v[148:151], v166 offset:53248
	ds_read_b128 v[152:155], v166 offset:53760
	ds_read_b128 v[156:159], v166 offset:54272
	ds_read_b128 v[160:163], v166 offset:54784
	s_waitcnt lgkmcnt(4)
	s_waitcnt vmcnt(7)
	v_mfma_f32_16x16x32_bf16 v[12:15], v[80:83], v[132:135], v[12:15]
	v_mfma_f32_16x16x32_bf16 v[8:11], v[80:83], v[136:139], v[8:11]
	v_mfma_f32_16x16x32_bf16 v[4:7], v[80:83], v[140:143], v[4:7]
	v_mfma_f32_16x16x32_bf16 v[0:3], v[80:83], v[144:147], v[0:3]
	s_waitcnt vmcnt(6)
	v_mfma_f32_16x16x32_bf16 v[28:31], v[84:87], v[132:135], v[28:31]
	v_mfma_f32_16x16x32_bf16 v[24:27], v[84:87], v[136:139], v[24:27]
	v_mfma_f32_16x16x32_bf16 v[20:23], v[84:87], v[140:143], v[20:23]
	v_mfma_f32_16x16x32_bf16 v[16:19], v[84:87], v[144:147], v[16:19]
	ds_read_b128 v[132:135], v166 offset:57344
	ds_read_b128 v[136:139], v166 offset:57856
	ds_read_b128 v[140:143], v166 offset:58368
	ds_read_b128 v[144:147], v166 offset:58880
	s_waitcnt lgkmcnt(4)
	s_waitcnt vmcnt(5)
	v_mfma_f32_16x16x32_bf16 v[12:15], v[88:91], v[148:151], v[12:15]
	v_mfma_f32_16x16x32_bf16 v[8:11], v[88:91], v[152:155], v[8:11]
	v_mfma_f32_16x16x32_bf16 v[4:7], v[88:91], v[156:159], v[4:7]
	v_mfma_f32_16x16x32_bf16 v[0:3], v[88:91], v[160:163], v[0:3]
	s_waitcnt vmcnt(4)
	v_mfma_f32_16x16x32_bf16 v[28:31], v[92:95], v[148:151], v[28:31]
	v_mfma_f32_16x16x32_bf16 v[24:27], v[92:95], v[152:155], v[24:27]
	v_mfma_f32_16x16x32_bf16 v[20:23], v[92:95], v[156:159], v[20:23]
	v_mfma_f32_16x16x32_bf16 v[16:19], v[92:95], v[160:163], v[16:19]
	ds_read_b128 v[148:151], v166 offset:61440
	ds_read_b128 v[152:155], v166 offset:61952
	ds_read_b128 v[156:159], v166 offset:62464
	ds_read_b128 v[160:163], v166 offset:62976
	s_waitcnt lgkmcnt(4)
	s_waitcnt vmcnt(3)
	v_mfma_f32_16x16x32_bf16 v[12:15], v[96:99], v[132:135], v[12:15]
	v_mfma_f32_16x16x32_bf16 v[8:11], v[96:99], v[136:139], v[8:11]
	v_mfma_f32_16x16x32_bf16 v[4:7], v[96:99], v[140:143], v[4:7]
	v_mfma_f32_16x16x32_bf16 v[0:3], v[96:99], v[144:147], v[0:3]
	s_waitcnt vmcnt(2)
	v_mfma_f32_16x16x32_bf16 v[28:31], v[100:103], v[132:135], v[28:31]
	v_mfma_f32_16x16x32_bf16 v[24:27], v[100:103], v[136:139], v[24:27]
	v_mfma_f32_16x16x32_bf16 v[20:23], v[100:103], v[140:143], v[20:23]
	v_mfma_f32_16x16x32_bf16 v[16:19], v[100:103], v[144:147], v[16:19]
	s_waitcnt lgkmcnt(0)
	s_waitcnt vmcnt(1)
	v_mfma_f32_16x16x32_bf16 v[12:15], v[104:107], v[148:151], v[12:15]
	v_mfma_f32_16x16x32_bf16 v[8:11], v[104:107], v[152:155], v[8:11]
	v_mfma_f32_16x16x32_bf16 v[4:7], v[104:107], v[156:159], v[4:7]
	v_mfma_f32_16x16x32_bf16 v[0:3], v[104:107], v[160:163], v[0:3]
	s_waitcnt vmcnt(0)
	v_mfma_f32_16x16x32_bf16 v[28:31], v[108:111], v[148:151], v[28:31]
	v_mfma_f32_16x16x32_bf16 v[24:27], v[108:111], v[152:155], v[24:27]
	v_mfma_f32_16x16x32_bf16 v[20:23], v[108:111], v[156:159], v[20:23]
	v_mfma_f32_16x16x32_bf16 v[16:19], v[108:111], v[160:163], v[16:19]
	s_mov_b32 s3, 0x10000
	v_lshl_or_b32 v38, s17, 11, v45
	v_add_u32_e32 v38, s16, v38
	v_ashrrev_i32_e32 v39, 31, v38
	v_lshlrev_b64 v[40:41], 10, v[38:39]
	v_lshl_add_u64 v[40:41], v[32:33], 0, v[40:41]
	s_barrier
	global_store_dwordx4 v[40:41], v[28:31], off
	s_add_i32 s54, s54, s76
	s_cmpk_gt_i32 s54, 0xff
	v_add_u32_e32 v28, 0x200, v38
	v_ashrrev_i32_e32 v29, 31, v28
	v_lshlrev_b64 v[28:29], 10, v[28:29]
	v_lshl_add_u64 v[28:29], v[32:33], 0, v[28:29]
	global_store_dwordx4 v[28:29], v[24:27], off
	s_nop 1
	v_add_u32_e32 v24, 0x400, v38
	v_ashrrev_i32_e32 v25, 31, v24
	v_lshlrev_b64 v[24:25], 10, v[24:25]
	v_lshl_add_u64 v[24:25], v[32:33], 0, v[24:25]
	global_store_dwordx4 v[24:25], v[20:23], off
	s_nop 1
	v_add_u32_e32 v20, 0x600, v38
	v_ashrrev_i32_e32 v21, 31, v20
	v_lshlrev_b64 v[20:21], 10, v[20:21]
	v_lshl_add_u64 v[20:21], v[32:33], 0, v[20:21]
	global_store_dwordx4 v[20:21], v[16:19], off
	global_store_dwordx4 v[40:41], v[12:15], off offset:64
	global_store_dwordx4 v[28:29], v[8:11], off offset:64
	global_store_dwordx4 v[24:25], v[4:7], off offset:64
	global_store_dwordx4 v[20:21], v[0:3], off offset:64
	s_cbranch_scc0 .LBB0_603
